# GDN chunk prep: 64x64 triangular solve as a blocked solve on the f32 matrix cores (v_mfma_f32_16x16x4_f32)
# speedup vs baseline: 1.0274x; 1.0106x over previous
.LBB0_383:
	s_or_b64 exec, exec, s[2:3]
	ds_write_b32 v67, v2 offset:52416
	v_mul_f32_e32 v2, v5, v3
	v_cvt_pk_bf16_f32 v2, v2, s0
	v_lshl_add_u32 v3, v74, 1, v6
	ds_write_b16 v3, v2
	v_lshrrev_b32_e32 v19, 2, v68
	v_and_b32_e32 v2, 0xfc, v68
	v_add_u32_e32 v6, v46, v2
	v_mul_u32_u24_e32 v2, 0x110, v19
	v_lshlrev_b32_e32 v18, 6, v43
	v_add3_u32 v14, v140, v2, v18
	ds_read_b128 v[2:5], v14 offset:17408
	ds_read_b32 v22, v6
	ds_read_b128 v[6:9], v14 offset:17424
	s_waitcnt lgkmcnt(11)
	ds_read_b128 v[10:13], v14 offset:17440
	ds_read_b128 v[14:17], v14 offset:17456
	s_waitcnt lgkmcnt(4)
	v_lshlrev_b32_e32 v20, 16, v2
	v_and_b32_e32 v21, 0xffff0000, v2
	v_lshlrev_b32_e32 v2, 16, v3
	v_and_b32_e32 v3, 0xffff0000, v3
	s_waitcnt lgkmcnt(3)
	v_pk_mul_f32 v[26:27], v[22:23], v[2:3] op_sel_hi:[0,1]
	v_lshlrev_b32_e32 v2, 16, v4
	v_and_b32_e32 v3, 0xffff0000, v4
	v_pk_mul_f32 v[28:29], v[22:23], v[2:3] op_sel_hi:[0,1]
	v_lshlrev_b32_e32 v2, 16, v5
	v_and_b32_e32 v3, 0xffff0000, v5
	v_pk_mul_f32 v[30:31], v[22:23], v[2:3] op_sel_hi:[0,1]
	s_waitcnt lgkmcnt(2)
	v_lshlrev_b32_e32 v2, 16, v6
	v_and_b32_e32 v3, 0xffff0000, v6
	v_pk_mul_f32 v[32:33], v[22:23], v[2:3] op_sel_hi:[0,1]
	v_lshlrev_b32_e32 v2, 16, v7
	v_and_b32_e32 v3, 0xffff0000, v7
	v_pk_mul_f32 v[6:7], v[22:23], v[2:3] op_sel_hi:[0,1]
	v_lshlrev_b32_e32 v2, 16, v8
	v_and_b32_e32 v3, 0xffff0000, v8
	v_pk_mul_f32 v[34:35], v[22:23], v[2:3] op_sel_hi:[0,1]
	v_lshlrev_b32_e32 v2, 16, v9
	v_and_b32_e32 v3, 0xffff0000, v9
	v_pk_mul_f32 v[8:9], v[22:23], v[2:3] op_sel_hi:[0,1]
	s_waitcnt lgkmcnt(1)
	v_lshlrev_b32_e32 v2, 16, v10
	v_and_b32_e32 v3, 0xffff0000, v10
	v_pk_mul_f32 v[4:5], v[22:23], v[2:3] op_sel_hi:[0,1]
	v_lshlrev_b32_e32 v2, 16, v11
	v_and_b32_e32 v3, 0xffff0000, v11
	v_pk_mul_f32 v[10:11], v[22:23], v[2:3] op_sel_hi:[0,1]
	v_lshlrev_b32_e32 v2, 16, v12
	v_and_b32_e32 v3, 0xffff0000, v12
	v_pk_mul_f32 v[36:37], v[22:23], v[2:3] op_sel_hi:[0,1]
	v_lshlrev_b32_e32 v2, 16, v13
	v_and_b32_e32 v3, 0xffff0000, v13
	v_pk_mul_f32 v[12:13], v[22:23], v[2:3] op_sel_hi:[0,1]
	v_lshlrev_b32_e32 v3, 5, v143
	v_and_b32_e32 v46, 32, v3
	v_pk_mul_f32 v[24:25], v[22:23], v[20:21] op_sel_hi:[0,1]
	v_add_u32_e32 v2, 0x12cfc, v140
	v_and_b32_e32 v3, 0xfe, v68
	v_mul_u32_u24_e32 v20, 0x110, v46
	v_add3_u32 v21, v140, v3, v20
	ds_read_b32 v20, v2
	ds_read_u16 v47, v21
	ds_read_u16 v48, v21 offset:272
	s_waitcnt lgkmcnt(3)
	v_lshlrev_b32_e32 v2, 16, v14
	v_and_b32_e32 v3, 0xffff0000, v14
	v_pk_mul_f32 v[38:39], v[22:23], v[2:3] op_sel_hi:[0,1]
	v_lshlrev_b32_e32 v2, 16, v15
	v_and_b32_e32 v3, 0xffff0000, v15
	v_pk_mul_f32 v[14:15], v[22:23], v[2:3] op_sel_hi:[0,1]
	v_lshlrev_b32_e32 v2, 16, v16
	v_and_b32_e32 v3, 0xffff0000, v16
	v_ashrrev_i32_e32 v43, 31, v42
	v_pk_mul_f32 v[40:41], v[22:23], v[2:3] op_sel_hi:[0,1]
	v_lshlrev_b32_e32 v2, 16, v17
	v_and_b32_e32 v3, 0xffff0000, v17
	v_lshlrev_b64 v[16:17], 13, v[42:43]
	v_lshlrev_b64 v[42:43], 14, v[42:43]
	v_pk_mul_f32 v[22:23], v[22:23], v[2:3] op_sel_hi:[0,1]
	v_lshl_add_u64 v[2:3], s[26:27], 0, v[42:43]
	v_lshlrev_b32_e32 v58, 8, v19
	v_lshl_add_u64 v[2:3], v[2:3], 0, v[58:59]
	v_mov_b32_e32 v19, v59
	v_lshl_add_u64 v[18:19], v[2:3], 0, v[18:19]
	v_cvt_pk_bf16_f32 v2, v24, v25
	v_cvt_pk_bf16_f32 v3, v26, v27
	v_cvt_pk_bf16_f32 v4, v4, v5
	v_cvt_pk_bf16_f32 v5, v10, v11
	global_store_dwordx4 v[18:19], v[2:5], off
	v_lshl_add_u64 v[10:11], s[28:29], 0, v[42:43]
	v_lshlrev_b32_e32 v145, 3, v68
	v_cvt_pk_bf16_f32 v2, v28, v29
	v_cvt_pk_bf16_f32 v3, v30, v31
	v_cvt_pk_bf16_f32 v4, v36, v37
	v_cvt_pk_bf16_f32 v5, v12, v13
	global_store_dwordx4 v[18:19], v[2:5], off offset:16
	v_cmp_gt_u32_e64 s[2:3], s85, v68
	s_nop 0
	v_cvt_pk_bf16_f32 v2, v32, v33
	v_cvt_pk_bf16_f32 v3, v6, v7
	v_cvt_pk_bf16_f32 v4, v38, v39
	v_cvt_pk_bf16_f32 v5, v14, v15
	global_store_dwordx4 v[18:19], v[2:5], off offset:32
	s_nop 1
	v_cvt_pk_bf16_f32 v5, v22, v23
	v_lshl_add_u32 v22, v46, 2, v45
	v_cvt_pk_bf16_f32 v3, v8, v9
	ds_read_b128 v[6:9], v22
	v_cvt_pk_bf16_f32 v2, v34, v35
	v_cvt_pk_bf16_f32 v4, v40, v41
	global_store_dwordx4 v[18:19], v[2:5], off offset:48
	s_nop 1
	v_lshlrev_b32_e32 v2, 6, v68
	v_and_b32_e32 v58, 0x3f80, v2
	ds_read_b128 v[2:5], v22 offset:16
	s_waitcnt lgkmcnt(1)
	v_sub_f32_e32 v6, v20, v6
	v_mul_f32_e32 v12, 0x3fb8aa3b, v6
	v_fma_f32 v13, v6, s67, -v12
	v_rndne_f32_e32 v14, v12
	v_fmac_f32_e32 v13, 0x32a5705f, v6
	v_sub_f32_e32 v12, v12, v14
	v_add_f32_e32 v12, v12, v13
	v_exp_f32_e32 v12, v12
	v_cvt_i32_f32_e32 v13, v14
	v_lshl_add_u64 v[10:11], v[10:11], 0, v[58:59]
	v_lshlrev_b32_e32 v58, 1, v46
	v_sub_f32_e32 v7, v20, v7
	v_lshl_add_u64 v[18:19], v[10:11], 0, v[58:59]
	v_mul_f32_e32 v11, 0x3fb8aa3b, v7
	v_ldexp_f32 v10, v12, v13
	v_fma_f32 v12, v7, s67, -v11
	v_rndne_f32_e32 v13, v11
	v_fmac_f32_e32 v12, 0x32a5705f, v7
	v_sub_f32_e32 v11, v11, v13
	v_add_f32_e32 v11, v11, v12
	v_exp_f32_e32 v11, v11
	v_cvt_i32_f32_e32 v12, v13
	v_cmp_ngt_f32_e32 vcc, s72, v6
	v_sub_f32_e32 v8, v20, v8
	v_sub_f32_e32 v9, v20, v9
	v_cndmask_b32_e32 v10, 0, v10, vcc
	v_cmp_nlt_f32_e32 vcc, s73, v6
	s_waitcnt lgkmcnt(0)
	v_sub_f32_e32 v2, v20, v2
	v_sub_f32_e32 v3, v20, v3
	v_cndmask_b32_e32 v6, v138, v10, vcc
	v_ldexp_f32 v10, v11, v12
	v_cmp_ngt_f32_e32 vcc, s72, v7
	v_lshlrev_b32_e32 v11, 16, v48
	v_sub_f32_e32 v4, v20, v4
	v_cndmask_b32_e32 v10, 0, v10, vcc
	v_cmp_nlt_f32_e32 vcc, s73, v7
	v_lshlrev_b32_e32 v58, 4, v68
	s_nop 0
	v_cndmask_b32_e32 v7, v138, v10, vcc
	v_mul_f32_e32 v10, 0x3fb8aa3b, v8
	v_fma_f32 v12, v8, s67, -v10
	v_rndne_f32_e32 v13, v10
	v_fmac_f32_e32 v12, 0x32a5705f, v8
	v_sub_f32_e32 v10, v10, v13
	v_add_f32_e32 v10, v10, v12
	v_exp_f32_e32 v12, v10
	v_cvt_i32_f32_e32 v13, v13
	v_lshlrev_b32_e32 v10, 16, v47
	v_pk_mul_f32 v[6:7], v[6:7], v[10:11]
	v_mul_f32_e32 v10, 0x3fb8aa3b, v9
	v_cvt_pk_bf16_f32 v6, v6, v7
	v_ldexp_f32 v7, v12, v13
	v_fma_f32 v11, v9, s67, -v10
	v_rndne_f32_e32 v12, v10
	v_fmac_f32_e32 v11, 0x32a5705f, v9
	v_sub_f32_e32 v10, v10, v12
	v_add_f32_e32 v10, v10, v11
	v_exp_f32_e32 v10, v10
	v_cvt_i32_f32_e32 v11, v12
	v_cmp_ngt_f32_e32 vcc, s72, v8
	s_nop 1
	v_cndmask_b32_e32 v7, 0, v7, vcc
	v_cmp_nlt_f32_e32 vcc, s73, v8
	s_nop 1
	v_cndmask_b32_e32 v24, v138, v7, vcc
	v_ldexp_f32 v7, v10, v11
	v_cmp_ngt_f32_e32 vcc, s72, v9
	s_nop 1
	v_cndmask_b32_e32 v7, 0, v7, vcc
	v_cmp_nlt_f32_e32 vcc, s73, v9
	s_nop 1
	v_cndmask_b32_e32 v25, v138, v7, vcc
	ds_read_b128 v[8:11], v22 offset:64
	ds_read_u16 v7, v21 offset:544
	ds_read_u16 v12, v21 offset:816
	ds_read_u16 v23, v21 offset:1088
	ds_read_u16 v28, v21 offset:1360
	ds_read_u16 v29, v21 offset:1632
	ds_read_u16 v30, v21 offset:1904
	ds_read_u16 v31, v21 offset:2176
	ds_read_u16 v32, v21 offset:2448
	s_waitcnt lgkmcnt(8)
	v_sub_f32_e32 v8, v20, v8
	v_mul_f32_e32 v26, 0x3fb8aa3b, v8
	v_fma_f32 v33, v8, s67, -v26
	v_rndne_f32_e32 v34, v26
	v_fmac_f32_e32 v33, 0x32a5705f, v8
	v_sub_f32_e32 v26, v26, v34
	v_add_f32_e32 v26, v26, v33
	s_waitcnt lgkmcnt(6)
	v_lshlrev_b32_e32 v27, 16, v12
	v_exp_f32_e32 v33, v26
	v_lshlrev_b32_e32 v26, 16, v7
	v_pk_mul_f32 v[24:25], v[24:25], v[26:27]
	v_sub_f32_e32 v9, v20, v9
	v_cvt_pk_bf16_f32 v7, v24, v25
	v_mul_f32_e32 v25, 0x3fb8aa3b, v9
	v_fma_f32 v26, v9, s67, -v25
	v_rndne_f32_e32 v27, v25
	v_cvt_i32_f32_e32 v34, v34
	v_fmac_f32_e32 v26, 0x32a5705f, v9
	v_sub_f32_e32 v25, v25, v27
	v_add_f32_e32 v25, v25, v26
	v_exp_f32_e32 v25, v25
	v_cvt_i32_f32_e32 v26, v27
	v_ldexp_f32 v24, v33, v34
	v_cmp_ngt_f32_e32 vcc, s72, v8
	v_sub_f32_e32 v10, v20, v10
	ds_read_b128 v[12:15], v22 offset:80
	v_cndmask_b32_e32 v24, 0, v24, vcc
	v_cmp_nlt_f32_e32 vcc, s73, v8
	v_sub_f32_e32 v11, v20, v11
	s_nop 0
	v_cndmask_b32_e32 v8, v138, v24, vcc
	v_ldexp_f32 v24, v25, v26
	v_cmp_ngt_f32_e32 vcc, s72, v9
	ds_read_u16 v25, v21 offset:4624
	s_waitcnt lgkmcnt(1)
	v_sub_f32_e32 v12, v20, v12
	v_cndmask_b32_e32 v24, 0, v24, vcc
	v_cmp_nlt_f32_e32 vcc, s73, v9
	s_waitcnt lgkmcnt(0)
	v_lshlrev_b32_e32 v25, 16, v25
	v_cndmask_b32_e32 v9, v138, v24, vcc
	v_mul_f32_e32 v24, 0x3fb8aa3b, v10
	v_fma_f32 v26, v10, s67, -v24
	v_rndne_f32_e32 v27, v24
	v_fmac_f32_e32 v26, 0x32a5705f, v10
	v_sub_f32_e32 v24, v24, v27
	v_add_f32_e32 v24, v24, v26
	v_exp_f32_e32 v26, v24
	v_cvt_i32_f32_e32 v27, v27
	ds_read_u16 v24, v21 offset:4352
	ds_read_u16 v33, v21 offset:2720
	ds_read_u16 v34, v21 offset:2992
	ds_read_u16 v35, v21 offset:3264
	ds_read_u16 v36, v21 offset:3536
	ds_read_u16 v37, v21 offset:3808
	ds_read_u16 v38, v21 offset:4080
	s_waitcnt lgkmcnt(6)
	v_lshlrev_b32_e32 v24, 16, v24
	v_pk_mul_f32 v[8:9], v[8:9], v[24:25]
	v_mul_f32_e32 v24, 0x3fb8aa3b, v11
	v_cvt_pk_bf16_f32 v8, v8, v9
	v_ldexp_f32 v9, v26, v27
	v_fma_f32 v25, v11, s67, -v24
	v_rndne_f32_e32 v26, v24
	v_fmac_f32_e32 v25, 0x32a5705f, v11
	v_sub_f32_e32 v24, v24, v26
	v_add_f32_e32 v24, v24, v25
	v_exp_f32_e32 v24, v24
	v_cvt_i32_f32_e32 v25, v26
	v_cmp_ngt_f32_e32 vcc, s72, v10
	s_nop 1
	v_cndmask_b32_e32 v9, 0, v9, vcc
	v_cmp_nlt_f32_e32 vcc, s73, v10
	s_nop 1
	v_cndmask_b32_e32 v10, v138, v9, vcc
	v_ldexp_f32 v9, v24, v25
	v_cmp_ngt_f32_e32 vcc, s72, v11
	s_nop 1
	v_cndmask_b32_e32 v9, 0, v9, vcc
	v_cmp_nlt_f32_e32 vcc, s73, v11
	s_nop 1
	v_cndmask_b32_e32 v11, v138, v9, vcc
	ds_read_u16 v9, v21 offset:4896
	ds_read_u16 v24, v21 offset:5168
	ds_read_u16 v26, v21 offset:5440
	ds_read_u16 v27, v21 offset:5712
	ds_read_u16 v39, v21 offset:5984
	ds_read_u16 v40, v21 offset:6256
	ds_read_u16 v41, v21 offset:6528
	ds_read_u16 v42, v21 offset:6800
	s_waitcnt lgkmcnt(6)
	v_lshlrev_b32_e32 v25, 16, v24
	v_lshlrev_b32_e32 v24, 16, v9
	v_mul_f32_e32 v9, 0x3fb8aa3b, v2
	v_pk_mul_f32 v[10:11], v[10:11], v[24:25]
	v_fma_f32 v24, v2, s67, -v9
	v_rndne_f32_e32 v25, v9
	v_fmac_f32_e32 v24, 0x32a5705f, v2
	v_sub_f32_e32 v9, v9, v25
	v_add_f32_e32 v9, v9, v24
	v_exp_f32_e32 v24, v9
	v_cvt_i32_f32_e32 v25, v25
	v_cvt_pk_bf16_f32 v9, v10, v11
	v_mul_f32_e32 v11, 0x3fb8aa3b, v3
	v_cmp_ngt_f32_e32 vcc, s72, v2
	v_ldexp_f32 v10, v24, v25
	v_fma_f32 v24, v3, s67, -v11
	v_rndne_f32_e32 v25, v11
	v_fmac_f32_e32 v24, 0x32a5705f, v3
	v_sub_f32_e32 v11, v11, v25
	v_add_f32_e32 v11, v11, v24
	v_exp_f32_e32 v11, v11
	v_cvt_i32_f32_e32 v24, v25
	v_cndmask_b32_e32 v10, 0, v10, vcc
	v_cmp_nlt_f32_e32 vcc, s73, v2
	global_store_dwordx4 v[18:19], v[6:9], off
	ds_read_b128 v[6:9], v22 offset:32
	v_cndmask_b32_e32 v2, v138, v10, vcc
	v_ldexp_f32 v10, v11, v24
	v_cmp_ngt_f32_e32 vcc, s72, v3
	v_lshlrev_b32_e32 v11, 16, v28
	s_nop 0
	v_cndmask_b32_e32 v10, 0, v10, vcc
	v_cmp_nlt_f32_e32 vcc, s73, v3
	s_nop 1
	v_cndmask_b32_e32 v3, v138, v10, vcc
	v_mul_f32_e32 v10, 0x3fb8aa3b, v4
	v_fma_f32 v24, v4, s67, -v10
	v_rndne_f32_e32 v25, v10
	v_fmac_f32_e32 v24, 0x32a5705f, v4
	v_sub_f32_e32 v10, v10, v25
	v_add_f32_e32 v10, v10, v24
	v_exp_f32_e32 v24, v10
	v_lshlrev_b32_e32 v10, 16, v23
	v_pk_mul_f32 v[2:3], v[2:3], v[10:11]
	v_cvt_i32_f32_e32 v25, v25
	v_cvt_pk_bf16_f32 v10, v2, v3
	v_sub_f32_e32 v3, v20, v5
	v_mul_f32_e32 v5, 0x3fb8aa3b, v3
	v_fma_f32 v11, v3, s67, -v5
	v_rndne_f32_e32 v23, v5
	v_fmac_f32_e32 v11, 0x32a5705f, v3
	v_sub_f32_e32 v5, v5, v23
	v_add_f32_e32 v5, v5, v11
	v_exp_f32_e32 v5, v5
	v_cvt_i32_f32_e32 v11, v23
	v_ldexp_f32 v2, v24, v25
	v_cmp_ngt_f32_e32 vcc, s72, v4
	s_waitcnt lgkmcnt(3)
	v_lshlrev_b32_e32 v25, 16, v40
	v_cndmask_b32_e32 v2, 0, v2, vcc
	v_cmp_nlt_f32_e32 vcc, s73, v4
	v_ldexp_f32 v4, v5, v11
	v_lshlrev_b32_e32 v5, 16, v30
	v_cndmask_b32_e32 v2, v138, v2, vcc
	v_cmp_ngt_f32_e32 vcc, s72, v3
	s_nop 1
	v_cndmask_b32_e32 v4, 0, v4, vcc
	v_cmp_nlt_f32_e32 vcc, s73, v3
	s_nop 1
	v_cndmask_b32_e32 v3, v138, v4, vcc
	v_mul_f32_e32 v4, 0x3fb8aa3b, v12
	v_fma_f32 v11, v12, s67, -v4
	v_rndne_f32_e32 v23, v4
	v_fmac_f32_e32 v11, 0x32a5705f, v12
	v_sub_f32_e32 v4, v4, v23
	v_add_f32_e32 v4, v4, v11
	v_exp_f32_e32 v24, v4
	v_lshlrev_b32_e32 v4, 16, v29
	v_pk_mul_f32 v[2:3], v[2:3], v[4:5]
	v_cvt_i32_f32_e32 v23, v23
	v_cvt_pk_bf16_f32 v11, v2, v3
	v_sub_f32_e32 v3, v20, v13
	v_mul_f32_e32 v4, 0x3fb8aa3b, v3
	v_fma_f32 v5, v3, s67, -v4
	v_rndne_f32_e32 v13, v4
	v_fmac_f32_e32 v5, 0x32a5705f, v3
	v_sub_f32_e32 v4, v4, v13
	v_add_f32_e32 v4, v4, v5
	v_exp_f32_e32 v4, v4
	v_cvt_i32_f32_e32 v5, v13
	v_ldexp_f32 v2, v24, v23
	v_cmp_ngt_f32_e32 vcc, s72, v12
	v_sub_f32_e32 v13, v20, v14
	v_ldexp_f32 v4, v4, v5
	v_cndmask_b32_e32 v2, 0, v2, vcc
	v_cmp_nlt_f32_e32 vcc, s73, v12
	v_lshlrev_b32_e32 v5, 16, v27
	v_lshlrev_b32_e32 v24, 16, v39
	v_cndmask_b32_e32 v2, v138, v2, vcc
	v_cmp_ngt_f32_e32 vcc, s72, v3
	s_nop 1
	v_cndmask_b32_e32 v4, 0, v4, vcc
	v_cmp_nlt_f32_e32 vcc, s73, v3
	s_nop 1
	v_cndmask_b32_e32 v3, v138, v4, vcc
	v_mul_f32_e32 v4, 0x3fb8aa3b, v13
	v_fma_f32 v12, v13, s67, -v4
	v_rndne_f32_e32 v14, v4
	v_fmac_f32_e32 v12, 0x32a5705f, v13
	v_sub_f32_e32 v4, v4, v14
	v_add_f32_e32 v4, v4, v12
	v_exp_f32_e32 v23, v4
	v_cvt_i32_f32_e32 v14, v14
	v_lshlrev_b32_e32 v4, 16, v26
	v_pk_mul_f32 v[2:3], v[2:3], v[4:5]
	v_cmp_ngt_f32_e32 vcc, s72, v13
	v_cvt_pk_bf16_f32 v12, v2, v3
	v_sub_f32_e32 v3, v20, v15
	v_mul_f32_e32 v4, 0x3fb8aa3b, v3
	v_ldexp_f32 v2, v23, v14
	v_fma_f32 v5, v3, s67, -v4
	v_rndne_f32_e32 v14, v4
	v_fmac_f32_e32 v5, 0x32a5705f, v3
	v_sub_f32_e32 v4, v4, v14
	v_add_f32_e32 v4, v4, v5
	v_exp_f32_e32 v4, v4
	v_cvt_i32_f32_e32 v5, v14
	v_cndmask_b32_e32 v2, 0, v2, vcc
	v_cmp_nlt_f32_e32 vcc, s73, v13
	s_nop 1
	v_cndmask_b32_e32 v14, v138, v2, vcc
	v_ldexp_f32 v2, v4, v5
	v_cmp_ngt_f32_e32 vcc, s72, v3
	s_nop 1
	v_cndmask_b32_e32 v2, 0, v2, vcc
	v_cmp_nlt_f32_e32 vcc, s73, v3
	s_nop 1
	v_cndmask_b32_e32 v15, v138, v2, vcc
	ds_read_b128 v[2:5], v22 offset:48
	s_waitcnt lgkmcnt(1)
	v_sub_f32_e32 v6, v20, v6
	v_mul_f32_e32 v13, 0x3fb8aa3b, v6
	v_fma_f32 v23, v6, s67, -v13
	v_rndne_f32_e32 v26, v13
	v_fmac_f32_e32 v23, 0x32a5705f, v6
	v_sub_f32_e32 v13, v13, v26
	v_add_f32_e32 v13, v13, v23
	v_pk_mul_f32 v[14:15], v[14:15], v[24:25]
	v_exp_f32_e32 v23, v13
	v_cvt_pk_bf16_f32 v13, v14, v15
	v_sub_f32_e32 v7, v20, v7
	global_store_dwordx4 v[18:19], v[10:13], off offset:16
	v_cvt_i32_f32_e32 v26, v26
	v_cmp_ngt_f32_e32 vcc, s72, v6
	v_mul_f32_e32 v11, 0x3fb8aa3b, v7
	v_fma_f32 v12, v7, s67, -v11
	v_rndne_f32_e32 v13, v11
	v_fmac_f32_e32 v12, 0x32a5705f, v7
	v_sub_f32_e32 v11, v11, v13
	v_add_f32_e32 v11, v11, v12
	v_exp_f32_e32 v11, v11
	v_cvt_i32_f32_e32 v12, v13
	v_ldexp_f32 v10, v23, v26
	v_cndmask_b32_e32 v10, 0, v10, vcc
	v_cmp_nlt_f32_e32 vcc, s73, v6
	v_sub_f32_e32 v8, v20, v8
	v_lshlrev_b32_e32 v23, 16, v34
	v_cndmask_b32_e32 v6, v138, v10, vcc
	v_ldexp_f32 v10, v11, v12
	v_cmp_ngt_f32_e32 vcc, s72, v7
	v_lshlrev_b32_e32 v11, 16, v32
	s_waitcnt lgkmcnt(0)
	v_sub_f32_e32 v2, v20, v2
	v_cndmask_b32_e32 v10, 0, v10, vcc
	v_cmp_nlt_f32_e32 vcc, s73, v7
	v_sub_f32_e32 v3, v20, v3
	v_sub_f32_e32 v4, v20, v4
	v_cndmask_b32_e32 v7, v138, v10, vcc
	v_mul_f32_e32 v10, 0x3fb8aa3b, v8
	v_fma_f32 v12, v8, s67, -v10
	v_rndne_f32_e32 v13, v10
	v_fmac_f32_e32 v12, 0x32a5705f, v8
	v_sub_f32_e32 v10, v10, v13
	v_add_f32_e32 v10, v10, v12
	v_exp_f32_e32 v12, v10
	v_cvt_i32_f32_e32 v13, v13
	v_lshlrev_b32_e32 v10, 16, v31
	v_pk_mul_f32 v[6:7], v[6:7], v[10:11]
	v_cmp_ngt_f32_e32 vcc, s72, v8
	v_cvt_pk_bf16_f32 v6, v6, v7
	v_ldexp_f32 v7, v12, v13
	v_sub_f32_e32 v12, v20, v9
	v_mul_f32_e32 v9, 0x3fb8aa3b, v12
	v_fma_f32 v10, v12, s67, -v9
	v_rndne_f32_e32 v11, v9
	v_fmac_f32_e32 v10, 0x32a5705f, v12
	v_sub_f32_e32 v9, v9, v11
	v_add_f32_e32 v9, v9, v10
	v_exp_f32_e32 v9, v9
	v_cvt_i32_f32_e32 v10, v11
	v_cndmask_b32_e32 v7, 0, v7, vcc
	v_cmp_nlt_f32_e32 vcc, s73, v8
	v_sub_f32_e32 v5, v20, v5
	s_nop 0
	v_cndmask_b32_e32 v24, v138, v7, vcc
	v_ldexp_f32 v7, v9, v10
	ds_read_b128 v[8:11], v22 offset:96
	v_cmp_ngt_f32_e32 vcc, s72, v12
	s_nop 1
	v_cndmask_b32_e32 v7, 0, v7, vcc
	v_cmp_nlt_f32_e32 vcc, s73, v12
	ds_read_b128 v[12:15], v22 offset:112
	s_waitcnt lgkmcnt(1)
	v_sub_f32_e32 v8, v20, v8
	v_cndmask_b32_e32 v25, v138, v7, vcc
	v_mul_f32_e32 v7, 0x3fb8aa3b, v8
	v_fma_f32 v22, v8, s67, -v7
	v_rndne_f32_e32 v26, v7
	v_fmac_f32_e32 v22, 0x32a5705f, v8
	v_sub_f32_e32 v7, v7, v26
	v_add_f32_e32 v7, v7, v22
	v_lshlrev_b32_e32 v22, 16, v33
	v_pk_mul_f32 v[22:23], v[24:25], v[22:23]
	v_sub_f32_e32 v9, v20, v9
	v_exp_f32_e32 v27, v7
	v_cvt_pk_bf16_f32 v7, v22, v23
	v_mul_f32_e32 v23, 0x3fb8aa3b, v9
	v_fma_f32 v24, v9, s67, -v23
	v_rndne_f32_e32 v25, v23
	v_cvt_i32_f32_e32 v26, v26
	v_fmac_f32_e32 v24, 0x32a5705f, v9
	v_sub_f32_e32 v23, v23, v25
	v_add_f32_e32 v23, v23, v24
	v_exp_f32_e32 v23, v23
	v_cvt_i32_f32_e32 v24, v25
	v_ldexp_f32 v22, v27, v26
	v_cmp_ngt_f32_e32 vcc, s72, v8
	v_sub_f32_e32 v10, v20, v10
	v_sub_f32_e32 v11, v20, v11
	v_cndmask_b32_e32 v22, 0, v22, vcc
	v_cmp_nlt_f32_e32 vcc, s73, v8
	s_nop 1
	v_cndmask_b32_e32 v8, v138, v22, vcc
	v_ldexp_f32 v22, v23, v24
	v_cmp_ngt_f32_e32 vcc, s72, v9
	v_lshlrev_b32_e32 v23, 16, v42
	s_nop 0
	v_cndmask_b32_e32 v22, 0, v22, vcc
	v_cmp_nlt_f32_e32 vcc, s73, v9
	s_nop 1
	v_cndmask_b32_e32 v9, v138, v22, vcc
	v_mul_f32_e32 v22, 0x3fb8aa3b, v10
	v_fma_f32 v24, v10, s67, -v22
	v_rndne_f32_e32 v25, v22
	v_fmac_f32_e32 v24, 0x32a5705f, v10
	v_sub_f32_e32 v22, v22, v25
	v_add_f32_e32 v22, v22, v24
	v_exp_f32_e32 v24, v22
	v_cvt_i32_f32_e32 v25, v25
	v_lshlrev_b32_e32 v22, 16, v41
	v_pk_mul_f32 v[8:9], v[8:9], v[22:23]
	v_mul_f32_e32 v22, 0x3fb8aa3b, v11
	v_cvt_pk_bf16_f32 v8, v8, v9
	v_ldexp_f32 v9, v24, v25
	v_fma_f32 v23, v11, s67, -v22
	v_rndne_f32_e32 v24, v22
	v_fmac_f32_e32 v23, 0x32a5705f, v11
	v_sub_f32_e32 v22, v22, v24
	v_add_f32_e32 v22, v22, v23
	v_exp_f32_e32 v22, v22
	v_cvt_i32_f32_e32 v23, v24
	v_cmp_ngt_f32_e32 vcc, s72, v10
	s_nop 1
	v_cndmask_b32_e32 v9, 0, v9, vcc
	v_cmp_nlt_f32_e32 vcc, s73, v10
	s_nop 1
	v_cndmask_b32_e32 v10, v138, v9, vcc
	v_ldexp_f32 v9, v22, v23
	v_cmp_ngt_f32_e32 vcc, s72, v11
	s_nop 1
	v_cndmask_b32_e32 v9, 0, v9, vcc
	v_cmp_nlt_f32_e32 vcc, s73, v11
	s_nop 1
	v_cndmask_b32_e32 v11, v138, v9, vcc
	ds_read_u16 v9, v21 offset:7072
	ds_read_u16 v22, v21 offset:7344
	ds_read_u16 v24, v21 offset:7616
	ds_read_u16 v25, v21 offset:7888
	ds_read_u16 v26, v21 offset:8160
	ds_read_u16 v21, v21 offset:8432
	s_waitcnt lgkmcnt(4)
	v_lshlrev_b32_e32 v23, 16, v22
	v_lshlrev_b32_e32 v22, 16, v9
	v_mul_f32_e32 v9, 0x3fb8aa3b, v2
	v_fma_f32 v27, v2, s67, -v9
	v_rndne_f32_e32 v28, v9
	v_fmac_f32_e32 v27, 0x32a5705f, v2
	v_sub_f32_e32 v9, v9, v28
	v_add_f32_e32 v9, v9, v27
	v_pk_mul_f32 v[10:11], v[10:11], v[22:23]
	v_exp_f32_e32 v27, v9
	v_cvt_pk_bf16_f32 v9, v10, v11
	global_store_dwordx4 v[18:19], v[6:9], off offset:32
	v_cvt_i32_f32_e32 v28, v28
	v_cmp_ngt_f32_e32 vcc, s72, v2
	v_mul_f32_e32 v7, 0x3fb8aa3b, v3
	v_fma_f32 v8, v3, s67, -v7
	v_rndne_f32_e32 v9, v7
	v_fmac_f32_e32 v8, 0x32a5705f, v3
	v_sub_f32_e32 v7, v7, v9
	v_add_f32_e32 v7, v7, v8
	v_exp_f32_e32 v7, v7
	v_cvt_i32_f32_e32 v8, v9
	v_ldexp_f32 v6, v27, v28
	v_cndmask_b32_e32 v6, 0, v6, vcc
	v_cmp_nlt_f32_e32 vcc, s73, v2
	s_nop 1
	v_cndmask_b32_e32 v2, v138, v6, vcc
	v_ldexp_f32 v6, v7, v8
	v_cmp_ngt_f32_e32 vcc, s72, v3
	v_lshlrev_b32_e32 v7, 16, v36
	s_nop 0
	v_cndmask_b32_e32 v6, 0, v6, vcc
	v_cmp_nlt_f32_e32 vcc, s73, v3
	s_nop 1
	v_cndmask_b32_e32 v3, v138, v6, vcc
	v_mul_f32_e32 v6, 0x3fb8aa3b, v4
	v_fma_f32 v8, v4, s67, -v6
	v_rndne_f32_e32 v9, v6
	v_fmac_f32_e32 v8, 0x32a5705f, v4
	v_sub_f32_e32 v6, v6, v9
	v_add_f32_e32 v6, v6, v8
	v_exp_f32_e32 v8, v6
	v_cvt_i32_f32_e32 v9, v9
	v_lshlrev_b32_e32 v6, 16, v35
	v_pk_mul_f32 v[2:3], v[2:3], v[6:7]
	v_mul_f32_e32 v6, 0x3fb8aa3b, v5
	v_cvt_pk_bf16_f32 v2, v2, v3
	v_ldexp_f32 v3, v8, v9
	v_fma_f32 v7, v5, s67, -v6
	v_rndne_f32_e32 v8, v6
	v_fmac_f32_e32 v7, 0x32a5705f, v5
	v_sub_f32_e32 v6, v6, v8
	v_add_f32_e32 v6, v6, v7
	v_exp_f32_e32 v6, v6
	v_cvt_i32_f32_e32 v7, v8
	v_cmp_ngt_f32_e32 vcc, s72, v4
	v_sub_f32_e32 v8, v20, v12
	s_nop 0
	v_cndmask_b32_e32 v3, 0, v3, vcc
	v_cmp_nlt_f32_e32 vcc, s73, v4
	s_nop 1
	v_cndmask_b32_e32 v4, v138, v3, vcc
	v_ldexp_f32 v3, v6, v7
	v_cmp_ngt_f32_e32 vcc, s72, v5
	v_lshlrev_b32_e32 v7, 16, v38
	s_nop 0
	v_cndmask_b32_e32 v3, 0, v3, vcc
	v_cmp_nlt_f32_e32 vcc, s73, v5
	s_nop 1
	v_cndmask_b32_e32 v5, v138, v3, vcc
	v_mul_f32_e32 v3, 0x3fb8aa3b, v8
	v_fma_f32 v6, v8, s67, -v3
	v_rndne_f32_e32 v9, v3
	v_fmac_f32_e32 v6, 0x32a5705f, v8
	v_sub_f32_e32 v3, v3, v9
	v_add_f32_e32 v3, v3, v6
	v_exp_f32_e32 v10, v3
	v_cvt_i32_f32_e32 v9, v9
	v_lshlrev_b32_e32 v6, 16, v37
	v_pk_mul_f32 v[4:5], v[4:5], v[6:7]
	v_cmp_ngt_f32_e32 vcc, s72, v8
	v_cvt_pk_bf16_f32 v3, v4, v5
	v_sub_f32_e32 v5, v20, v13
	v_mul_f32_e32 v6, 0x3fb8aa3b, v5
	v_ldexp_f32 v4, v10, v9
	v_fma_f32 v7, v5, s67, -v6
	v_rndne_f32_e32 v9, v6
	v_fmac_f32_e32 v7, 0x32a5705f, v5
	v_sub_f32_e32 v6, v6, v9
	v_add_f32_e32 v6, v6, v7
	v_exp_f32_e32 v6, v6
	v_cvt_i32_f32_e32 v7, v9
	v_cndmask_b32_e32 v4, 0, v4, vcc
	v_cmp_nlt_f32_e32 vcc, s73, v8
	v_sub_f32_e32 v8, v20, v14
	v_ldexp_f32 v6, v6, v7
	v_cndmask_b32_e32 v4, v138, v4, vcc
	v_cmp_ngt_f32_e32 vcc, s72, v5
	s_waitcnt lgkmcnt(2)
	v_lshlrev_b32_e32 v7, 16, v25
	v_cndmask_b32_e32 v6, 0, v6, vcc
	v_cmp_nlt_f32_e32 vcc, s73, v5
	s_nop 1
	v_cndmask_b32_e32 v5, v138, v6, vcc
	v_mul_f32_e32 v6, 0x3fb8aa3b, v8
	v_fma_f32 v9, v8, s67, -v6
	v_rndne_f32_e32 v10, v6
	v_fmac_f32_e32 v9, 0x32a5705f, v8
	v_sub_f32_e32 v6, v6, v10
	v_add_f32_e32 v6, v6, v9
	v_exp_f32_e32 v9, v6
	v_cvt_i32_f32_e32 v10, v10
	v_lshlrev_b32_e32 v6, 16, v24
	v_pk_mul_f32 v[4:5], v[4:5], v[6:7]
	v_sub_f32_e32 v7, v20, v15
	v_mul_f32_e32 v6, 0x3fb8aa3b, v7
	v_cvt_pk_bf16_f32 v4, v4, v5
	v_ldexp_f32 v5, v9, v10
	v_fma_f32 v9, v7, s67, -v6
	v_rndne_f32_e32 v10, v6
	v_fmac_f32_e32 v9, 0x32a5705f, v7
	v_sub_f32_e32 v6, v6, v10
	v_add_f32_e32 v6, v6, v9
	v_exp_f32_e32 v9, v6
	v_cvt_i32_f32_e32 v10, v10
	v_cmp_ngt_f32_e32 vcc, s72, v8
	s_nop 1
	v_cndmask_b32_e32 v5, 0, v5, vcc
	v_cmp_nlt_f32_e32 vcc, s73, v8
	s_waitcnt lgkmcnt(1)
	v_lshlrev_b32_e32 v8, 16, v26
	v_cndmask_b32_e32 v6, v138, v5, vcc
	v_ldexp_f32 v5, v9, v10
	v_cmp_ngt_f32_e32 vcc, s72, v7
	s_waitcnt lgkmcnt(0)
	v_lshlrev_b32_e32 v9, 16, v21
	v_lshl_add_u64 v[10:11], s[30:31], 0, v[16:17]
	v_cndmask_b32_e32 v5, 0, v5, vcc
	v_cmp_nlt_f32_e32 vcc, s73, v7
	s_nop 1
	v_cndmask_b32_e32 v7, v138, v5, vcc
	v_pk_mul_f32 v[6:7], v[6:7], v[8:9]
	v_cmp_lt_u32_e32 vcc, s84, v68
	v_cvt_pk_bf16_f32 v5, v6, v7
	global_store_dwordx4 v[18:19], v[2:5], off offset:48
	v_or_b32_e32 v6, 0x800, v145
	s_nop 0
	v_add_u32_e32 v2, v44, v58
	s_barrier
	ds_read_b128 v[2:5], v2
	v_lshl_add_u64 v[18:19], v[10:11], 0, v[58:59]
	v_lshlrev_b32_e32 v58, 1, v6
	v_add_u32_e32 v6, v44, v58
	ds_read_b128 v[6:9], v6
	ds_read_b128 v[12:15], v140 offset:52992
	s_waitcnt lgkmcnt(2)
	global_store_dwordx4 v[18:19], v[2:5], off
	s_nop 1
	v_lshl_add_u64 v[2:3], v[10:11], 0, v[58:59]
	s_waitcnt lgkmcnt(1)
	global_store_dwordx4 v[2:3], v[6:9], off
	v_and_b32_e32 v2, 63, v143
	v_and_b32_e32 v3, 15, v143
	v_bfe_u32 v4, v143, 4, 2
	v_readfirstlane_b32 s0, v143
	s_nop 3
	s_bfe_u32 s0, s0, 0x20006
	s_mul_i32 s1, s0, 0x1040
	v_add_u32_e32 v10, 0xcc00, v140
	v_add_u32_e32 v10, s1, v10
	v_lshl_add_u32 v11, v3, 2, v10
	v_cmp_eq_u32_e32 vcc, 0, v3
	s_nop 1
	v_cndmask_b32_e64 v18, 0, 1.0, vcc
	ds_write_b32 v11, v18
	v_cmp_eq_u32_e32 vcc, 1, v3
	ds_read_b128 v[34:37], v10 offset:256
	s_nop 1
	v_cndmask_b32_e64 v19, 0, 1.0, vcc
	s_waitcnt lgkmcnt(0)
	v_fma_f32 v19, -v34, v18, v19
	ds_write_b32 v11, v19 offset:256
	v_cmp_eq_u32_e32 vcc, 2, v3
	ds_read_b128 v[34:37], v10 offset:512
	s_nop 1
	v_cndmask_b32_e64 v20, 0, 1.0, vcc
	s_waitcnt lgkmcnt(0)
	v_fma_f32 v20, -v34, v18, v20
	v_fma_f32 v20, -v35, v19, v20
	ds_write_b32 v11, v20 offset:512
	v_cmp_eq_u32_e32 vcc, 3, v3
	ds_read_b128 v[34:37], v10 offset:768
	s_nop 1
	v_cndmask_b32_e64 v21, 0, 1.0, vcc
	s_waitcnt lgkmcnt(0)
	v_fma_f32 v21, -v34, v18, v21
	v_fma_f32 v21, -v35, v19, v21
	v_fma_f32 v21, -v36, v20, v21
	ds_write_b32 v11, v21 offset:768
	v_cmp_eq_u32_e32 vcc, 4, v3
	ds_read_b128 v[34:37], v10 offset:1024
	s_nop 1
	v_cndmask_b32_e64 v22, 0, 1.0, vcc
	s_waitcnt lgkmcnt(0)
	v_fma_f32 v22, -v34, v18, v22
	v_fma_f32 v22, -v35, v19, v22
	v_fma_f32 v22, -v36, v20, v22
	v_fma_f32 v22, -v37, v21, v22
	ds_write_b32 v11, v22 offset:1024
	v_cmp_eq_u32_e32 vcc, 5, v3
	ds_read_b128 v[34:37], v10 offset:1280
	ds_read_b128 v[38:41], v10 offset:1296
	s_nop 1
	v_cndmask_b32_e64 v23, 0, 1.0, vcc
	s_waitcnt lgkmcnt(0)
	v_fma_f32 v23, -v34, v18, v23
	v_fma_f32 v23, -v35, v19, v23
	v_fma_f32 v23, -v36, v20, v23
	v_fma_f32 v23, -v37, v21, v23
	v_fma_f32 v23, -v38, v22, v23
	ds_write_b32 v11, v23 offset:1280
	v_cmp_eq_u32_e32 vcc, 6, v3
	ds_read_b128 v[34:37], v10 offset:1536
	ds_read_b128 v[38:41], v10 offset:1552
	s_nop 1
	v_cndmask_b32_e64 v24, 0, 1.0, vcc
	s_waitcnt lgkmcnt(0)
	v_fma_f32 v24, -v34, v18, v24
	v_fma_f32 v24, -v35, v19, v24
	v_fma_f32 v24, -v36, v20, v24
	v_fma_f32 v24, -v37, v21, v24
	v_fma_f32 v24, -v38, v22, v24
	v_fma_f32 v24, -v39, v23, v24
	ds_write_b32 v11, v24 offset:1536
	v_cmp_eq_u32_e32 vcc, 7, v3
	ds_read_b128 v[34:37], v10 offset:1792
	ds_read_b128 v[38:41], v10 offset:1808
	s_nop 1
	v_cndmask_b32_e64 v25, 0, 1.0, vcc
	s_waitcnt lgkmcnt(0)
	v_fma_f32 v25, -v34, v18, v25
	v_fma_f32 v25, -v35, v19, v25
	v_fma_f32 v25, -v36, v20, v25
	v_fma_f32 v25, -v37, v21, v25
	v_fma_f32 v25, -v38, v22, v25
	v_fma_f32 v25, -v39, v23, v25
	v_fma_f32 v25, -v40, v24, v25
	ds_write_b32 v11, v25 offset:1792
	v_cmp_eq_u32_e32 vcc, 8, v3
	ds_read_b128 v[34:37], v10 offset:2048
	ds_read_b128 v[38:41], v10 offset:2064
	s_nop 1
	v_cndmask_b32_e64 v26, 0, 1.0, vcc
	s_waitcnt lgkmcnt(0)
	v_fma_f32 v26, -v34, v18, v26
	v_fma_f32 v26, -v35, v19, v26
	v_fma_f32 v26, -v36, v20, v26
	v_fma_f32 v26, -v37, v21, v26
	v_fma_f32 v26, -v38, v22, v26
	v_fma_f32 v26, -v39, v23, v26
	v_fma_f32 v26, -v40, v24, v26
	v_fma_f32 v26, -v41, v25, v26
	ds_write_b32 v11, v26 offset:2048
	v_cmp_eq_u32_e32 vcc, 9, v3
	ds_read_b128 v[34:37], v10 offset:2304
	ds_read_b128 v[38:41], v10 offset:2320
	ds_read_b128 v[42:45], v10 offset:2336
	s_nop 1
	v_cndmask_b32_e64 v27, 0, 1.0, vcc
	s_waitcnt lgkmcnt(0)
	v_fma_f32 v27, -v34, v18, v27
	v_fma_f32 v27, -v35, v19, v27
	v_fma_f32 v27, -v36, v20, v27
	v_fma_f32 v27, -v37, v21, v27
	v_fma_f32 v27, -v38, v22, v27
	v_fma_f32 v27, -v39, v23, v27
	v_fma_f32 v27, -v40, v24, v27
	v_fma_f32 v27, -v41, v25, v27
	v_fma_f32 v27, -v42, v26, v27
	ds_write_b32 v11, v27 offset:2304
	v_cmp_eq_u32_e32 vcc, 10, v3
	ds_read_b128 v[34:37], v10 offset:2560
	ds_read_b128 v[38:41], v10 offset:2576
	ds_read_b128 v[42:45], v10 offset:2592
	s_nop 1
	v_cndmask_b32_e64 v28, 0, 1.0, vcc
	s_waitcnt lgkmcnt(0)
	v_fma_f32 v28, -v34, v18, v28
	v_fma_f32 v28, -v35, v19, v28
	v_fma_f32 v28, -v36, v20, v28
	v_fma_f32 v28, -v37, v21, v28
	v_fma_f32 v28, -v38, v22, v28
	v_fma_f32 v28, -v39, v23, v28
	v_fma_f32 v28, -v40, v24, v28
	v_fma_f32 v28, -v41, v25, v28
	v_fma_f32 v28, -v42, v26, v28
	v_fma_f32 v28, -v43, v27, v28
	ds_write_b32 v11, v28 offset:2560
	v_cmp_eq_u32_e32 vcc, 11, v3
	ds_read_b128 v[34:37], v10 offset:2816
	ds_read_b128 v[38:41], v10 offset:2832
	ds_read_b128 v[42:45], v10 offset:2848
	s_nop 1
	v_cndmask_b32_e64 v29, 0, 1.0, vcc
	s_waitcnt lgkmcnt(0)
	v_fma_f32 v29, -v34, v18, v29
	v_fma_f32 v29, -v35, v19, v29
	v_fma_f32 v29, -v36, v20, v29
	v_fma_f32 v29, -v37, v21, v29
	v_fma_f32 v29, -v38, v22, v29
	v_fma_f32 v29, -v39, v23, v29
	v_fma_f32 v29, -v40, v24, v29
	v_fma_f32 v29, -v41, v25, v29
	v_fma_f32 v29, -v42, v26, v29
	v_fma_f32 v29, -v43, v27, v29
	v_fma_f32 v29, -v44, v28, v29
	ds_write_b32 v11, v29 offset:2816
	v_cmp_eq_u32_e32 vcc, 12, v3
	ds_read_b128 v[34:37], v10 offset:3072
	ds_read_b128 v[38:41], v10 offset:3088
	ds_read_b128 v[42:45], v10 offset:3104
	s_nop 1
	v_cndmask_b32_e64 v30, 0, 1.0, vcc
	s_waitcnt lgkmcnt(0)
	v_fma_f32 v30, -v34, v18, v30
	v_fma_f32 v30, -v35, v19, v30
	v_fma_f32 v30, -v36, v20, v30
	v_fma_f32 v30, -v37, v21, v30
	v_fma_f32 v30, -v38, v22, v30
	v_fma_f32 v30, -v39, v23, v30
	v_fma_f32 v30, -v40, v24, v30
	v_fma_f32 v30, -v41, v25, v30
	v_fma_f32 v30, -v42, v26, v30
	v_fma_f32 v30, -v43, v27, v30
	v_fma_f32 v30, -v44, v28, v30
	v_fma_f32 v30, -v45, v29, v30
	ds_write_b32 v11, v30 offset:3072
	v_cmp_eq_u32_e32 vcc, 13, v3
	ds_read_b128 v[34:37], v10 offset:3328
	ds_read_b128 v[38:41], v10 offset:3344
	ds_read_b128 v[42:45], v10 offset:3360
	ds_read_b128 v[46:49], v10 offset:3376
	s_nop 1
	v_cndmask_b32_e64 v31, 0, 1.0, vcc
	s_waitcnt lgkmcnt(0)
	v_fma_f32 v31, -v34, v18, v31
	v_fma_f32 v31, -v35, v19, v31
	v_fma_f32 v31, -v36, v20, v31
	v_fma_f32 v31, -v37, v21, v31
	v_fma_f32 v31, -v38, v22, v31
	v_fma_f32 v31, -v39, v23, v31
	v_fma_f32 v31, -v40, v24, v31
	v_fma_f32 v31, -v41, v25, v31
	v_fma_f32 v31, -v42, v26, v31
	v_fma_f32 v31, -v43, v27, v31
	v_fma_f32 v31, -v44, v28, v31
	v_fma_f32 v31, -v45, v29, v31
	v_fma_f32 v31, -v46, v30, v31
	ds_write_b32 v11, v31 offset:3328
	v_cmp_eq_u32_e32 vcc, 14, v3
	ds_read_b128 v[34:37], v10 offset:3584
	ds_read_b128 v[38:41], v10 offset:3600
	ds_read_b128 v[42:45], v10 offset:3616
	ds_read_b128 v[46:49], v10 offset:3632
	s_nop 1
	v_cndmask_b32_e64 v32, 0, 1.0, vcc
	s_waitcnt lgkmcnt(0)
	v_fma_f32 v32, -v34, v18, v32
	v_fma_f32 v32, -v35, v19, v32
	v_fma_f32 v32, -v36, v20, v32
	v_fma_f32 v32, -v37, v21, v32
	v_fma_f32 v32, -v38, v22, v32
	v_fma_f32 v32, -v39, v23, v32
	v_fma_f32 v32, -v40, v24, v32
	v_fma_f32 v32, -v41, v25, v32
	v_fma_f32 v32, -v42, v26, v32
	v_fma_f32 v32, -v43, v27, v32
	v_fma_f32 v32, -v44, v28, v32
	v_fma_f32 v32, -v45, v29, v32
	v_fma_f32 v32, -v46, v30, v32
	v_fma_f32 v32, -v47, v31, v32
	ds_write_b32 v11, v32 offset:3584
	v_cmp_eq_u32_e32 vcc, 15, v3
	ds_read_b128 v[34:37], v10 offset:3840
	ds_read_b128 v[38:41], v10 offset:3856
	ds_read_b128 v[42:45], v10 offset:3872
	ds_read_b128 v[46:49], v10 offset:3888
	s_nop 1
	v_cndmask_b32_e64 v33, 0, 1.0, vcc
	s_waitcnt lgkmcnt(0)
	v_fma_f32 v33, -v34, v18, v33
	v_fma_f32 v33, -v35, v19, v33
	v_fma_f32 v33, -v36, v20, v33
	v_fma_f32 v33, -v37, v21, v33
	v_fma_f32 v33, -v38, v22, v33
	v_fma_f32 v33, -v39, v23, v33
	v_fma_f32 v33, -v40, v24, v33
	v_fma_f32 v33, -v41, v25, v33
	v_fma_f32 v33, -v42, v26, v33
	v_fma_f32 v33, -v43, v27, v33
	v_fma_f32 v33, -v44, v28, v33
	v_fma_f32 v33, -v45, v29, v33
	v_fma_f32 v33, -v46, v30, v33
	v_fma_f32 v33, -v47, v31, v33
	v_fma_f32 v33, -v48, v32, v33
	ds_write_b32 v11, v33 offset:3840
	s_waitcnt lgkmcnt(0)
	s_barrier
	v_mul_u32_u24_e32 v12, 0x440, v4
	v_lshl_add_u32 v12, v3, 1, v12
	s_and_b32 s1, s0, 1
	s_lshl_b32 s1, s1, 7
	s_cmp_lt_u32 s0, 2
	s_cselect_b32 s2, 0x8800, 0
	s_add_i32 s1, s1, s2
	v_add3_u32 v7, v140, v12, s1
	s_mov_b32 s1, 0x12f00
	s_cmp_lt_u32 s0, 2
	s_cselect_b32 s1, 0x12d00, s1
	v_lshl_add_u32 v8, v4, 4, v140
	v_add_u32_e32 v8, s1, v8
	v_lshl_add_u32 v6, v3, 8, v140
	v_lshl_add_u32 v6, v4, 4, v6
	v_add_u32_e32 v6, 0xcc00, v6
	ds_read_b128 v[50:53], v8 offset:0
	ds_read_u16 v62, v7 offset:0
	ds_read_u16 v63, v7 offset:272
	ds_read_u16 v64, v7 offset:544
	ds_read_u16 v65, v7 offset:816
	ds_read_u16 v66, v7 offset:32
	ds_read_u16 v67, v7 offset:304
	ds_read_u16 v68, v7 offset:576
	ds_read_u16 v69, v7 offset:848
	s_waitcnt lgkmcnt(0)
	ds_read_u16 v70, v7 offset:64
	ds_read_u16 v71, v7 offset:336
	ds_read_u16 v72, v7 offset:608
	ds_read_u16 v73, v7 offset:880
	ds_read_u16 v74, v7 offset:96
	ds_read_u16 v75, v7 offset:368
	ds_read_u16 v76, v7 offset:640
	ds_read_u16 v77, v7 offset:912
	s_waitcnt lgkmcnt(0)
	v_lshlrev_b32_e32 v62, 16, v62
	v_lshlrev_b32_e32 v63, 16, v63
	v_lshlrev_b32_e32 v64, 16, v64
	v_lshlrev_b32_e32 v65, 16, v65
	v_lshlrev_b32_e32 v66, 16, v66
	v_lshlrev_b32_e32 v67, 16, v67
	v_lshlrev_b32_e32 v68, 16, v68
	v_lshlrev_b32_e32 v69, 16, v69
	v_lshlrev_b32_e32 v70, 16, v70
	v_lshlrev_b32_e32 v71, 16, v71
	v_lshlrev_b32_e32 v72, 16, v72
	v_lshlrev_b32_e32 v73, 16, v73
	v_lshlrev_b32_e32 v74, 16, v74
	v_lshlrev_b32_e32 v75, 16, v75
	v_lshlrev_b32_e32 v76, 16, v76
	v_lshlrev_b32_e32 v77, 16, v77
	v_mul_f32_e32 v62, v50, v62
	v_mul_f32_e32 v63, v51, v63
	v_mul_f32_e32 v64, v52, v64
	v_mul_f32_e32 v65, v53, v65
	v_mul_f32_e32 v66, v50, v66
	v_mul_f32_e32 v67, v51, v67
	v_mul_f32_e32 v68, v52, v68
	v_mul_f32_e32 v69, v53, v69
	v_mul_f32_e32 v70, v50, v70
	v_mul_f32_e32 v71, v51, v71
	v_mul_f32_e32 v72, v52, v72
	v_mul_f32_e32 v73, v53, v73
	v_mul_f32_e32 v74, v50, v74
	v_mul_f32_e32 v75, v51, v75
	v_mul_f32_e32 v76, v52, v76
	v_mul_f32_e32 v77, v53, v77
	ds_read_b128 v[50:53], v8 offset:64
	ds_read_u16 v78, v7 offset:4352
	ds_read_u16 v79, v7 offset:4624
	ds_read_u16 v80, v7 offset:4896
	ds_read_u16 v81, v7 offset:5168
	ds_read_u16 v82, v7 offset:4384
	ds_read_u16 v83, v7 offset:4656
	ds_read_u16 v84, v7 offset:4928
	ds_read_u16 v85, v7 offset:5200
	s_waitcnt lgkmcnt(0)
	ds_read_u16 v86, v7 offset:4416
	ds_read_u16 v87, v7 offset:4688
	ds_read_u16 v88, v7 offset:4960
	ds_read_u16 v89, v7 offset:5232
	ds_read_u16 v90, v7 offset:4448
	ds_read_u16 v91, v7 offset:4720
	ds_read_u16 v92, v7 offset:4992
	ds_read_u16 v93, v7 offset:5264
	s_waitcnt lgkmcnt(0)
	v_lshlrev_b32_e32 v78, 16, v78
	v_lshlrev_b32_e32 v79, 16, v79
	v_lshlrev_b32_e32 v80, 16, v80
	v_lshlrev_b32_e32 v81, 16, v81
	v_lshlrev_b32_e32 v82, 16, v82
	v_lshlrev_b32_e32 v83, 16, v83
	v_lshlrev_b32_e32 v84, 16, v84
	v_lshlrev_b32_e32 v85, 16, v85
	v_lshlrev_b32_e32 v86, 16, v86
	v_lshlrev_b32_e32 v87, 16, v87
	v_lshlrev_b32_e32 v88, 16, v88
	v_lshlrev_b32_e32 v89, 16, v89
	v_lshlrev_b32_e32 v90, 16, v90
	v_lshlrev_b32_e32 v91, 16, v91
	v_lshlrev_b32_e32 v92, 16, v92
	v_lshlrev_b32_e32 v93, 16, v93
	v_mul_f32_e32 v78, v50, v78
	v_mul_f32_e32 v79, v51, v79
	v_mul_f32_e32 v80, v52, v80
	v_mul_f32_e32 v81, v53, v81
	v_mul_f32_e32 v82, v50, v82
	v_mul_f32_e32 v83, v51, v83
	v_mul_f32_e32 v84, v52, v84
	v_mul_f32_e32 v85, v53, v85
	v_mul_f32_e32 v86, v50, v86
	v_mul_f32_e32 v87, v51, v87
	v_mul_f32_e32 v88, v52, v88
	v_mul_f32_e32 v89, v53, v89
	v_mul_f32_e32 v90, v50, v90
	v_mul_f32_e32 v91, v51, v91
	v_mul_f32_e32 v92, v52, v92
	v_mul_f32_e32 v93, v53, v93
	ds_read_b128 v[50:53], v8 offset:128
	ds_read_u16 v94, v7 offset:8704
	ds_read_u16 v95, v7 offset:8976
	ds_read_u16 v96, v7 offset:9248
	ds_read_u16 v97, v7 offset:9520
	ds_read_u16 v98, v7 offset:8736
	ds_read_u16 v99, v7 offset:9008
	ds_read_u16 v100, v7 offset:9280
	ds_read_u16 v101, v7 offset:9552
	s_waitcnt lgkmcnt(0)
	ds_read_u16 v102, v7 offset:8768
	ds_read_u16 v103, v7 offset:9040
	ds_read_u16 v104, v7 offset:9312
	ds_read_u16 v105, v7 offset:9584
	ds_read_u16 v106, v7 offset:8800
	ds_read_u16 v107, v7 offset:9072
	ds_read_u16 v108, v7 offset:9344
	ds_read_u16 v109, v7 offset:9616
	s_waitcnt lgkmcnt(0)
	v_lshlrev_b32_e32 v94, 16, v94
	v_lshlrev_b32_e32 v95, 16, v95
	v_lshlrev_b32_e32 v96, 16, v96
	v_lshlrev_b32_e32 v97, 16, v97
	v_lshlrev_b32_e32 v98, 16, v98
	v_lshlrev_b32_e32 v99, 16, v99
	v_lshlrev_b32_e32 v100, 16, v100
	v_lshlrev_b32_e32 v101, 16, v101
	v_lshlrev_b32_e32 v102, 16, v102
	v_lshlrev_b32_e32 v103, 16, v103
	v_lshlrev_b32_e32 v104, 16, v104
	v_lshlrev_b32_e32 v105, 16, v105
	v_lshlrev_b32_e32 v106, 16, v106
	v_lshlrev_b32_e32 v107, 16, v107
	v_lshlrev_b32_e32 v108, 16, v108
	v_lshlrev_b32_e32 v109, 16, v109
	v_mul_f32_e32 v94, v50, v94
	v_mul_f32_e32 v95, v51, v95
	v_mul_f32_e32 v96, v52, v96
	v_mul_f32_e32 v97, v53, v97
	v_mul_f32_e32 v98, v50, v98
	v_mul_f32_e32 v99, v51, v99
	v_mul_f32_e32 v100, v52, v100
	v_mul_f32_e32 v101, v53, v101
	v_mul_f32_e32 v102, v50, v102
	v_mul_f32_e32 v103, v51, v103
	v_mul_f32_e32 v104, v52, v104
	v_mul_f32_e32 v105, v53, v105
	v_mul_f32_e32 v106, v50, v106
	v_mul_f32_e32 v107, v51, v107
	v_mul_f32_e32 v108, v52, v108
	v_mul_f32_e32 v109, v53, v109
	ds_read_b128 v[50:53], v8 offset:192
	ds_read_u16 v110, v7 offset:13056
	ds_read_u16 v111, v7 offset:13328
	ds_read_u16 v112, v7 offset:13600
	ds_read_u16 v113, v7 offset:13872
	ds_read_u16 v114, v7 offset:13088
	ds_read_u16 v115, v7 offset:13360
	ds_read_u16 v116, v7 offset:13632
	ds_read_u16 v117, v7 offset:13904
	s_waitcnt lgkmcnt(0)
	ds_read_u16 v118, v7 offset:13120
	ds_read_u16 v119, v7 offset:13392
	ds_read_u16 v120, v7 offset:13664
	ds_read_u16 v121, v7 offset:13936
	ds_read_u16 v122, v7 offset:13152
	ds_read_u16 v123, v7 offset:13424
	ds_read_u16 v124, v7 offset:13696
	ds_read_u16 v125, v7 offset:13968
	s_waitcnt lgkmcnt(0)
	v_lshlrev_b32_e32 v110, 16, v110
	v_lshlrev_b32_e32 v111, 16, v111
	v_lshlrev_b32_e32 v112, 16, v112
	v_lshlrev_b32_e32 v113, 16, v113
	v_lshlrev_b32_e32 v114, 16, v114
	v_lshlrev_b32_e32 v115, 16, v115
	v_lshlrev_b32_e32 v116, 16, v116
	v_lshlrev_b32_e32 v117, 16, v117
	v_lshlrev_b32_e32 v118, 16, v118
	v_lshlrev_b32_e32 v119, 16, v119
	v_lshlrev_b32_e32 v120, 16, v120
	v_lshlrev_b32_e32 v121, 16, v121
	v_lshlrev_b32_e32 v122, 16, v122
	v_lshlrev_b32_e32 v123, 16, v123
	v_lshlrev_b32_e32 v124, 16, v124
	v_lshlrev_b32_e32 v125, 16, v125
	v_mul_f32_e32 v110, v50, v110
	v_mul_f32_e32 v111, v51, v111
	v_mul_f32_e32 v112, v52, v112
	v_mul_f32_e32 v113, v53, v113
	v_mul_f32_e32 v114, v50, v114
	v_mul_f32_e32 v115, v51, v115
	v_mul_f32_e32 v116, v52, v116
	v_mul_f32_e32 v117, v53, v117
	v_mul_f32_e32 v118, v50, v118
	v_mul_f32_e32 v119, v51, v119
	v_mul_f32_e32 v120, v52, v120
	v_mul_f32_e32 v121, v53, v121
	v_mul_f32_e32 v122, v50, v122
	v_mul_f32_e32 v123, v51, v123
	v_mul_f32_e32 v124, v52, v124
	v_mul_f32_e32 v125, v53, v125
	s_nop 1
	ds_read_b128 v[42:45], v6 offset:0
	s_waitcnt lgkmcnt(0)
	v_mfma_f32_16x16x4_f32 v[18:21], v42, v62, 0
	v_mfma_f32_16x16x4_f32 v[22:25], v42, v66, 0
	v_mfma_f32_16x16x4_f32 v[26:29], v42, v70, 0
	v_mfma_f32_16x16x4_f32 v[30:33], v42, v74, 0
	v_mfma_f32_16x16x4_f32 v[18:21], v43, v63, v[18:21]
	v_mfma_f32_16x16x4_f32 v[22:25], v43, v67, v[22:25]
	v_mfma_f32_16x16x4_f32 v[26:29], v43, v71, v[26:29]
	v_mfma_f32_16x16x4_f32 v[30:33], v43, v75, v[30:33]
	v_mfma_f32_16x16x4_f32 v[18:21], v44, v64, v[18:21]
	v_mfma_f32_16x16x4_f32 v[22:25], v44, v68, v[22:25]
	v_mfma_f32_16x16x4_f32 v[26:29], v44, v72, v[26:29]
	v_mfma_f32_16x16x4_f32 v[30:33], v44, v76, v[30:33]
	v_mfma_f32_16x16x4_f32 v[18:21], v45, v65, v[18:21]
	v_mfma_f32_16x16x4_f32 v[22:25], v45, v69, v[22:25]
	v_mfma_f32_16x16x4_f32 v[26:29], v45, v73, v[26:29]
	v_mfma_f32_16x16x4_f32 v[30:33], v45, v77, v[30:33]
	s_nop 9
	ds_read_b128 v[34:37], v6 offset:4096
	s_waitcnt lgkmcnt(0)
	v_xor_b32_e32 v34, 0x80000000, v34
	v_xor_b32_e32 v35, 0x80000000, v35
	v_xor_b32_e32 v36, 0x80000000, v36
	v_xor_b32_e32 v37, 0x80000000, v37
	s_nop 1
	v_mfma_f32_16x16x4_f32 v[78:81], v34, v18, v[78:81]
	v_mfma_f32_16x16x4_f32 v[82:85], v34, v22, v[82:85]
	v_mfma_f32_16x16x4_f32 v[86:89], v34, v26, v[86:89]
	v_mfma_f32_16x16x4_f32 v[90:93], v34, v30, v[90:93]
	v_mfma_f32_16x16x4_f32 v[78:81], v35, v19, v[78:81]
	v_mfma_f32_16x16x4_f32 v[82:85], v35, v23, v[82:85]
	v_mfma_f32_16x16x4_f32 v[86:89], v35, v27, v[86:89]
	v_mfma_f32_16x16x4_f32 v[90:93], v35, v31, v[90:93]
	v_mfma_f32_16x16x4_f32 v[78:81], v36, v20, v[78:81]
	v_mfma_f32_16x16x4_f32 v[82:85], v36, v24, v[82:85]
	v_mfma_f32_16x16x4_f32 v[86:89], v36, v28, v[86:89]
	v_mfma_f32_16x16x4_f32 v[90:93], v36, v32, v[90:93]
	v_mfma_f32_16x16x4_f32 v[78:81], v37, v21, v[78:81]
	v_mfma_f32_16x16x4_f32 v[82:85], v37, v25, v[82:85]
	v_mfma_f32_16x16x4_f32 v[86:89], v37, v29, v[86:89]
	v_mfma_f32_16x16x4_f32 v[90:93], v37, v33, v[90:93]
	ds_read_b128 v[34:37], v6 offset:8192
	s_waitcnt lgkmcnt(0)
	v_xor_b32_e32 v34, 0x80000000, v34
	v_xor_b32_e32 v35, 0x80000000, v35
	v_xor_b32_e32 v36, 0x80000000, v36
	v_xor_b32_e32 v37, 0x80000000, v37
	s_nop 1
	v_mfma_f32_16x16x4_f32 v[94:97], v34, v18, v[94:97]
	v_mfma_f32_16x16x4_f32 v[98:101], v34, v22, v[98:101]
	v_mfma_f32_16x16x4_f32 v[102:105], v34, v26, v[102:105]
	v_mfma_f32_16x16x4_f32 v[106:109], v34, v30, v[106:109]
	v_mfma_f32_16x16x4_f32 v[94:97], v35, v19, v[94:97]
	v_mfma_f32_16x16x4_f32 v[98:101], v35, v23, v[98:101]
	v_mfma_f32_16x16x4_f32 v[102:105], v35, v27, v[102:105]
	v_mfma_f32_16x16x4_f32 v[106:109], v35, v31, v[106:109]
	v_mfma_f32_16x16x4_f32 v[94:97], v36, v20, v[94:97]
	v_mfma_f32_16x16x4_f32 v[98:101], v36, v24, v[98:101]
	v_mfma_f32_16x16x4_f32 v[102:105], v36, v28, v[102:105]
	v_mfma_f32_16x16x4_f32 v[106:109], v36, v32, v[106:109]
	v_mfma_f32_16x16x4_f32 v[94:97], v37, v21, v[94:97]
	v_mfma_f32_16x16x4_f32 v[98:101], v37, v25, v[98:101]
	v_mfma_f32_16x16x4_f32 v[102:105], v37, v29, v[102:105]
	v_mfma_f32_16x16x4_f32 v[106:109], v37, v33, v[106:109]
	ds_read_b128 v[34:37], v6 offset:12288
	s_waitcnt lgkmcnt(0)
	v_xor_b32_e32 v34, 0x80000000, v34
	v_xor_b32_e32 v35, 0x80000000, v35
	v_xor_b32_e32 v36, 0x80000000, v36
	v_xor_b32_e32 v37, 0x80000000, v37
	s_nop 1
	v_mfma_f32_16x16x4_f32 v[110:113], v34, v18, v[110:113]
	v_mfma_f32_16x16x4_f32 v[114:117], v34, v22, v[114:117]
	v_mfma_f32_16x16x4_f32 v[118:121], v34, v26, v[118:121]
	v_mfma_f32_16x16x4_f32 v[122:125], v34, v30, v[122:125]
	v_mfma_f32_16x16x4_f32 v[110:113], v35, v19, v[110:113]
	v_mfma_f32_16x16x4_f32 v[114:117], v35, v23, v[114:117]
	v_mfma_f32_16x16x4_f32 v[118:121], v35, v27, v[118:121]
	v_mfma_f32_16x16x4_f32 v[122:125], v35, v31, v[122:125]
	v_mfma_f32_16x16x4_f32 v[110:113], v36, v20, v[110:113]
	v_mfma_f32_16x16x4_f32 v[114:117], v36, v24, v[114:117]
	v_mfma_f32_16x16x4_f32 v[118:121], v36, v28, v[118:121]
	v_mfma_f32_16x16x4_f32 v[122:125], v36, v32, v[122:125]
	v_mfma_f32_16x16x4_f32 v[110:113], v37, v21, v[110:113]
	v_mfma_f32_16x16x4_f32 v[114:117], v37, v25, v[114:117]
	v_mfma_f32_16x16x4_f32 v[118:121], v37, v29, v[118:121]
	v_mfma_f32_16x16x4_f32 v[122:125], v37, v33, v[122:125]
	ds_read_b128 v[42:45], v6 offset:4160
	s_waitcnt lgkmcnt(0)
	v_mfma_f32_16x16x4_f32 v[62:65], v42, v78, 0
	v_mfma_f32_16x16x4_f32 v[66:69], v42, v82, 0
	v_mfma_f32_16x16x4_f32 v[70:73], v42, v86, 0
	v_mfma_f32_16x16x4_f32 v[74:77], v42, v90, 0
	v_mfma_f32_16x16x4_f32 v[62:65], v43, v79, v[62:65]
	v_mfma_f32_16x16x4_f32 v[66:69], v43, v83, v[66:69]
	v_mfma_f32_16x16x4_f32 v[70:73], v43, v87, v[70:73]
	v_mfma_f32_16x16x4_f32 v[74:77], v43, v91, v[74:77]
	v_mfma_f32_16x16x4_f32 v[62:65], v44, v80, v[62:65]
	v_mfma_f32_16x16x4_f32 v[66:69], v44, v84, v[66:69]
	v_mfma_f32_16x16x4_f32 v[70:73], v44, v88, v[70:73]
	v_mfma_f32_16x16x4_f32 v[74:77], v44, v92, v[74:77]
	v_mfma_f32_16x16x4_f32 v[62:65], v45, v81, v[62:65]
	v_mfma_f32_16x16x4_f32 v[66:69], v45, v85, v[66:69]
	v_mfma_f32_16x16x4_f32 v[70:73], v45, v89, v[70:73]
	v_mfma_f32_16x16x4_f32 v[74:77], v45, v93, v[74:77]
	s_nop 9
	ds_read_b128 v[34:37], v6 offset:8256
	s_waitcnt lgkmcnt(0)
	v_xor_b32_e32 v34, 0x80000000, v34
	v_xor_b32_e32 v35, 0x80000000, v35
	v_xor_b32_e32 v36, 0x80000000, v36
	v_xor_b32_e32 v37, 0x80000000, v37
	s_nop 1
	v_mfma_f32_16x16x4_f32 v[94:97], v34, v62, v[94:97]
	v_mfma_f32_16x16x4_f32 v[98:101], v34, v66, v[98:101]
	v_mfma_f32_16x16x4_f32 v[102:105], v34, v70, v[102:105]
	v_mfma_f32_16x16x4_f32 v[106:109], v34, v74, v[106:109]
	v_mfma_f32_16x16x4_f32 v[94:97], v35, v63, v[94:97]
	v_mfma_f32_16x16x4_f32 v[98:101], v35, v67, v[98:101]
	v_mfma_f32_16x16x4_f32 v[102:105], v35, v71, v[102:105]
	v_mfma_f32_16x16x4_f32 v[106:109], v35, v75, v[106:109]
	v_mfma_f32_16x16x4_f32 v[94:97], v36, v64, v[94:97]
	v_mfma_f32_16x16x4_f32 v[98:101], v36, v68, v[98:101]
	v_mfma_f32_16x16x4_f32 v[102:105], v36, v72, v[102:105]
	v_mfma_f32_16x16x4_f32 v[106:109], v36, v76, v[106:109]
	v_mfma_f32_16x16x4_f32 v[94:97], v37, v65, v[94:97]
	v_mfma_f32_16x16x4_f32 v[98:101], v37, v69, v[98:101]
	v_mfma_f32_16x16x4_f32 v[102:105], v37, v73, v[102:105]
	v_mfma_f32_16x16x4_f32 v[106:109], v37, v77, v[106:109]
	ds_read_b128 v[34:37], v6 offset:12352
	s_waitcnt lgkmcnt(0)
	v_xor_b32_e32 v34, 0x80000000, v34
	v_xor_b32_e32 v35, 0x80000000, v35
	v_xor_b32_e32 v36, 0x80000000, v36
	v_xor_b32_e32 v37, 0x80000000, v37
	s_nop 1
	v_mfma_f32_16x16x4_f32 v[110:113], v34, v62, v[110:113]
	v_mfma_f32_16x16x4_f32 v[114:117], v34, v66, v[114:117]
	v_mfma_f32_16x16x4_f32 v[118:121], v34, v70, v[118:121]
	v_mfma_f32_16x16x4_f32 v[122:125], v34, v74, v[122:125]
	v_mfma_f32_16x16x4_f32 v[110:113], v35, v63, v[110:113]
	v_mfma_f32_16x16x4_f32 v[114:117], v35, v67, v[114:117]
	v_mfma_f32_16x16x4_f32 v[118:121], v35, v71, v[118:121]
	v_mfma_f32_16x16x4_f32 v[122:125], v35, v75, v[122:125]
	v_mfma_f32_16x16x4_f32 v[110:113], v36, v64, v[110:113]
	v_mfma_f32_16x16x4_f32 v[114:117], v36, v68, v[114:117]
	v_mfma_f32_16x16x4_f32 v[118:121], v36, v72, v[118:121]
	v_mfma_f32_16x16x4_f32 v[122:125], v36, v76, v[122:125]
	v_mfma_f32_16x16x4_f32 v[110:113], v37, v65, v[110:113]
	v_mfma_f32_16x16x4_f32 v[114:117], v37, v69, v[114:117]
	v_mfma_f32_16x16x4_f32 v[118:121], v37, v73, v[118:121]
	v_mfma_f32_16x16x4_f32 v[122:125], v37, v77, v[122:125]
	ds_read_b128 v[42:45], v6 offset:8320
	s_waitcnt lgkmcnt(0)
	v_mfma_f32_16x16x4_f32 v[78:81], v42, v94, 0
	v_mfma_f32_16x16x4_f32 v[82:85], v42, v98, 0
	v_mfma_f32_16x16x4_f32 v[86:89], v42, v102, 0
	v_mfma_f32_16x16x4_f32 v[90:93], v42, v106, 0
	v_mfma_f32_16x16x4_f32 v[78:81], v43, v95, v[78:81]
	v_mfma_f32_16x16x4_f32 v[82:85], v43, v99, v[82:85]
	v_mfma_f32_16x16x4_f32 v[86:89], v43, v103, v[86:89]
	v_mfma_f32_16x16x4_f32 v[90:93], v43, v107, v[90:93]
	v_mfma_f32_16x16x4_f32 v[78:81], v44, v96, v[78:81]
	v_mfma_f32_16x16x4_f32 v[82:85], v44, v100, v[82:85]
	v_mfma_f32_16x16x4_f32 v[86:89], v44, v104, v[86:89]
	v_mfma_f32_16x16x4_f32 v[90:93], v44, v108, v[90:93]
	v_mfma_f32_16x16x4_f32 v[78:81], v45, v97, v[78:81]
	v_mfma_f32_16x16x4_f32 v[82:85], v45, v101, v[82:85]
	v_mfma_f32_16x16x4_f32 v[86:89], v45, v105, v[86:89]
	v_mfma_f32_16x16x4_f32 v[90:93], v45, v109, v[90:93]
	s_nop 9
	ds_read_b128 v[34:37], v6 offset:12416
	s_waitcnt lgkmcnt(0)
	v_xor_b32_e32 v34, 0x80000000, v34
	v_xor_b32_e32 v35, 0x80000000, v35
	v_xor_b32_e32 v36, 0x80000000, v36
	v_xor_b32_e32 v37, 0x80000000, v37
	s_nop 1
	v_mfma_f32_16x16x4_f32 v[110:113], v34, v78, v[110:113]
	v_mfma_f32_16x16x4_f32 v[114:117], v34, v82, v[114:117]
	v_mfma_f32_16x16x4_f32 v[118:121], v34, v86, v[118:121]
	v_mfma_f32_16x16x4_f32 v[122:125], v34, v90, v[122:125]
	v_mfma_f32_16x16x4_f32 v[110:113], v35, v79, v[110:113]
	v_mfma_f32_16x16x4_f32 v[114:117], v35, v83, v[114:117]
	v_mfma_f32_16x16x4_f32 v[118:121], v35, v87, v[118:121]
	v_mfma_f32_16x16x4_f32 v[122:125], v35, v91, v[122:125]
	v_mfma_f32_16x16x4_f32 v[110:113], v36, v80, v[110:113]
	v_mfma_f32_16x16x4_f32 v[114:117], v36, v84, v[114:117]
	v_mfma_f32_16x16x4_f32 v[118:121], v36, v88, v[118:121]
	v_mfma_f32_16x16x4_f32 v[122:125], v36, v92, v[122:125]
	v_mfma_f32_16x16x4_f32 v[110:113], v37, v81, v[110:113]
	v_mfma_f32_16x16x4_f32 v[114:117], v37, v85, v[114:117]
	v_mfma_f32_16x16x4_f32 v[118:121], v37, v89, v[118:121]
	v_mfma_f32_16x16x4_f32 v[122:125], v37, v93, v[122:125]
	s_nop 9
	ds_read_b128 v[42:45], v6 offset:12480
	s_waitcnt lgkmcnt(0)
	v_mfma_f32_16x16x4_f32 v[94:97], v42, v110, 0
	v_mfma_f32_16x16x4_f32 v[98:101], v42, v114, 0
	v_mfma_f32_16x16x4_f32 v[102:105], v42, v118, 0
	v_mfma_f32_16x16x4_f32 v[106:109], v42, v122, 0
	v_mfma_f32_16x16x4_f32 v[94:97], v43, v111, v[94:97]
	v_mfma_f32_16x16x4_f32 v[98:101], v43, v115, v[98:101]
	v_mfma_f32_16x16x4_f32 v[102:105], v43, v119, v[102:105]
	v_mfma_f32_16x16x4_f32 v[106:109], v43, v123, v[106:109]
	v_mfma_f32_16x16x4_f32 v[94:97], v44, v112, v[94:97]
	v_mfma_f32_16x16x4_f32 v[98:101], v44, v116, v[98:101]
	v_mfma_f32_16x16x4_f32 v[102:105], v44, v120, v[102:105]
	v_mfma_f32_16x16x4_f32 v[106:109], v44, v124, v[106:109]
	v_mfma_f32_16x16x4_f32 v[94:97], v45, v113, v[94:97]
	v_mfma_f32_16x16x4_f32 v[98:101], v45, v117, v[98:101]
	v_mfma_f32_16x16x4_f32 v[102:105], v45, v121, v[102:105]
	v_mfma_f32_16x16x4_f32 v[106:109], v45, v125, v[106:109]
	s_nop 11
	s_waitcnt lgkmcnt(0)
	s_barrier
	s_cmp_lt_u32 s0, 2
	s_cbranch_scc0 .Lg1m_wn
	s_lshl_b32 s1, s0, 13
	s_addk_i32 s1, 0x4000
	v_lshlrev_b32_e32 v9, 7, v4
	v_lshl_add_u32 v9, v3, 3, v9
	v_add3_u32 v9, v140, v9, s1
	v_cvt_pk_bf16_f32 v12, v18, v19
	v_cvt_pk_bf16_f32 v13, v20, v21
	ds_write_b64 v9, v[12:13] offset:0
	v_cvt_pk_bf16_f32 v14, v22, v23
	v_cvt_pk_bf16_f32 v15, v24, v25
	ds_write_b64 v9, v[14:15] offset:2048
	v_cvt_pk_bf16_f32 v12, v26, v27
	v_cvt_pk_bf16_f32 v13, v28, v29
	ds_write_b64 v9, v[12:13] offset:4096
	v_cvt_pk_bf16_f32 v14, v30, v31
	v_cvt_pk_bf16_f32 v15, v32, v33
	ds_write_b64 v9, v[14:15] offset:6144
	v_cvt_pk_bf16_f32 v12, v62, v63
	v_cvt_pk_bf16_f32 v13, v64, v65
	ds_write_b64 v9, v[12:13] offset:512
	v_cvt_pk_bf16_f32 v14, v66, v67
	v_cvt_pk_bf16_f32 v15, v68, v69
	ds_write_b64 v9, v[14:15] offset:2560
	v_cvt_pk_bf16_f32 v12, v70, v71
	v_cvt_pk_bf16_f32 v13, v72, v73
	ds_write_b64 v9, v[12:13] offset:4608
	v_cvt_pk_bf16_f32 v14, v74, v75
	v_cvt_pk_bf16_f32 v15, v76, v77
	ds_write_b64 v9, v[14:15] offset:6656
	v_cvt_pk_bf16_f32 v12, v78, v79
	v_cvt_pk_bf16_f32 v13, v80, v81
	ds_write_b64 v9, v[12:13] offset:1024
	v_cvt_pk_bf16_f32 v14, v82, v83
	v_cvt_pk_bf16_f32 v15, v84, v85
	ds_write_b64 v9, v[14:15] offset:3072
	v_cvt_pk_bf16_f32 v12, v86, v87
	v_cvt_pk_bf16_f32 v13, v88, v89
	ds_write_b64 v9, v[12:13] offset:5120
	v_cvt_pk_bf16_f32 v14, v90, v91
	v_cvt_pk_bf16_f32 v15, v92, v93
	ds_write_b64 v9, v[14:15] offset:7168
	v_cvt_pk_bf16_f32 v12, v94, v95
	v_cvt_pk_bf16_f32 v13, v96, v97
	ds_write_b64 v9, v[12:13] offset:1536
	v_cvt_pk_bf16_f32 v14, v98, v99
	v_cvt_pk_bf16_f32 v15, v100, v101
	ds_write_b64 v9, v[14:15] offset:3584
	v_cvt_pk_bf16_f32 v12, v102, v103
	v_cvt_pk_bf16_f32 v13, v104, v105
	ds_write_b64 v9, v[12:13] offset:5632
	v_cvt_pk_bf16_f32 v14, v106, v107
	v_cvt_pk_bf16_f32 v15, v108, v109
	ds_write_b64 v9, v[14:15] offset:7680
	s_branch .Lg1m_done
.Lg1m_wn:
	s_sub_i32 s1, s0, 2
	s_lshl_b32 s1, s1, 7
	v_lshlrev_b32_e32 v9, 10, v4
	v_lshrrev_b32_e32 v12, 2, v3
	v_lshl_add_u32 v9, v12, 4, v9
	v_and_b32_e32 v12, 3, v3
	v_lshl_add_u32 v9, v12, 1, v9
	v_add3_u32 v9, v140, v9, s1
	v_cvt_pk_bf16_f32 v12, -v18, v59
	ds_write_b16 v9, v12 offset:0
	v_cvt_pk_bf16_f32 v13, -v19, v59
	ds_write_b16 v9, v13 offset:256
	v_cvt_pk_bf16_f32 v14, -v20, v59
	ds_write_b16 v9, v14 offset:512
	v_cvt_pk_bf16_f32 v15, -v21, v59
	ds_write_b16 v9, v15 offset:768
	v_cvt_pk_bf16_f32 v12, -v22, v59
	ds_write_b16 v9, v12 offset:8
	v_cvt_pk_bf16_f32 v13, -v23, v59
	ds_write_b16 v9, v13 offset:264
	v_cvt_pk_bf16_f32 v14, -v24, v59
	ds_write_b16 v9, v14 offset:520
	v_cvt_pk_bf16_f32 v15, -v25, v59
	ds_write_b16 v9, v15 offset:776
	v_cvt_pk_bf16_f32 v12, -v26, v59
	ds_write_b16 v9, v12 offset:64
	v_cvt_pk_bf16_f32 v13, -v27, v59
	ds_write_b16 v9, v13 offset:320
	v_cvt_pk_bf16_f32 v14, -v28, v59
	ds_write_b16 v9, v14 offset:576
	v_cvt_pk_bf16_f32 v15, -v29, v59
	ds_write_b16 v9, v15 offset:832
	v_cvt_pk_bf16_f32 v12, -v30, v59
	ds_write_b16 v9, v12 offset:72
	v_cvt_pk_bf16_f32 v13, -v31, v59
	ds_write_b16 v9, v13 offset:328
	v_cvt_pk_bf16_f32 v14, -v32, v59
	ds_write_b16 v9, v14 offset:584
	v_cvt_pk_bf16_f32 v15, -v33, v59
	ds_write_b16 v9, v15 offset:840
	v_cvt_pk_bf16_f32 v12, -v62, v59
	ds_write_b16 v9, v12 offset:4096
	v_cvt_pk_bf16_f32 v13, -v63, v59
	ds_write_b16 v9, v13 offset:4352
	v_cvt_pk_bf16_f32 v14, -v64, v59
	ds_write_b16 v9, v14 offset:4608
	v_cvt_pk_bf16_f32 v15, -v65, v59
	ds_write_b16 v9, v15 offset:4864
	v_cvt_pk_bf16_f32 v12, -v66, v59
	ds_write_b16 v9, v12 offset:4104
	v_cvt_pk_bf16_f32 v13, -v67, v59
	ds_write_b16 v9, v13 offset:4360
	v_cvt_pk_bf16_f32 v14, -v68, v59
	ds_write_b16 v9, v14 offset:4616
	v_cvt_pk_bf16_f32 v15, -v69, v59
	ds_write_b16 v9, v15 offset:4872
	v_cvt_pk_bf16_f32 v12, -v70, v59
	ds_write_b16 v9, v12 offset:4160
	v_cvt_pk_bf16_f32 v13, -v71, v59
	ds_write_b16 v9, v13 offset:4416
	v_cvt_pk_bf16_f32 v14, -v72, v59
	ds_write_b16 v9, v14 offset:4672
	v_cvt_pk_bf16_f32 v15, -v73, v59
	ds_write_b16 v9, v15 offset:4928
	v_cvt_pk_bf16_f32 v12, -v74, v59
	ds_write_b16 v9, v12 offset:4168
	v_cvt_pk_bf16_f32 v13, -v75, v59
	ds_write_b16 v9, v13 offset:4424
	v_cvt_pk_bf16_f32 v14, -v76, v59
	ds_write_b16 v9, v14 offset:4680
	v_cvt_pk_bf16_f32 v15, -v77, v59
	ds_write_b16 v9, v15 offset:4936
	v_cvt_pk_bf16_f32 v12, -v78, v59
	ds_write_b16 v9, v12 offset:8192
	v_cvt_pk_bf16_f32 v13, -v79, v59
	ds_write_b16 v9, v13 offset:8448
	v_cvt_pk_bf16_f32 v14, -v80, v59
	ds_write_b16 v9, v14 offset:8704
	v_cvt_pk_bf16_f32 v15, -v81, v59
	ds_write_b16 v9, v15 offset:8960
	v_cvt_pk_bf16_f32 v12, -v82, v59
	ds_write_b16 v9, v12 offset:8200
	v_cvt_pk_bf16_f32 v13, -v83, v59
	ds_write_b16 v9, v13 offset:8456
	v_cvt_pk_bf16_f32 v14, -v84, v59
	ds_write_b16 v9, v14 offset:8712
	v_cvt_pk_bf16_f32 v15, -v85, v59
	ds_write_b16 v9, v15 offset:8968
	v_cvt_pk_bf16_f32 v12, -v86, v59
	ds_write_b16 v9, v12 offset:8256
	v_cvt_pk_bf16_f32 v13, -v87, v59
	ds_write_b16 v9, v13 offset:8512
	v_cvt_pk_bf16_f32 v14, -v88, v59
	ds_write_b16 v9, v14 offset:8768
	v_cvt_pk_bf16_f32 v15, -v89, v59
	ds_write_b16 v9, v15 offset:9024
	v_cvt_pk_bf16_f32 v12, -v90, v59
	ds_write_b16 v9, v12 offset:8264
	v_cvt_pk_bf16_f32 v13, -v91, v59
	ds_write_b16 v9, v13 offset:8520
	v_cvt_pk_bf16_f32 v14, -v92, v59
	ds_write_b16 v9, v14 offset:8776
	v_cvt_pk_bf16_f32 v15, -v93, v59
	ds_write_b16 v9, v15 offset:9032
	v_cvt_pk_bf16_f32 v12, -v94, v59
	ds_write_b16 v9, v12 offset:12288
	v_cvt_pk_bf16_f32 v13, -v95, v59
	ds_write_b16 v9, v13 offset:12544
	v_cvt_pk_bf16_f32 v14, -v96, v59
	ds_write_b16 v9, v14 offset:12800
	v_cvt_pk_bf16_f32 v15, -v97, v59
	ds_write_b16 v9, v15 offset:13056
	v_cvt_pk_bf16_f32 v12, -v98, v59
	ds_write_b16 v9, v12 offset:12296
	v_cvt_pk_bf16_f32 v13, -v99, v59
	ds_write_b16 v9, v13 offset:12552
	v_cvt_pk_bf16_f32 v14, -v100, v59
	ds_write_b16 v9, v14 offset:12808
	v_cvt_pk_bf16_f32 v15, -v101, v59
	ds_write_b16 v9, v15 offset:13064
	v_cvt_pk_bf16_f32 v12, -v102, v59
	ds_write_b16 v9, v12 offset:12352
	v_cvt_pk_bf16_f32 v13, -v103, v59
	ds_write_b16 v9, v13 offset:12608
	v_cvt_pk_bf16_f32 v14, -v104, v59
	ds_write_b16 v9, v14 offset:12864
	v_cvt_pk_bf16_f32 v15, -v105, v59
	ds_write_b16 v9, v15 offset:13120
	v_cvt_pk_bf16_f32 v12, -v106, v59
	ds_write_b16 v9, v12 offset:12360
	v_cvt_pk_bf16_f32 v13, -v107, v59
	ds_write_b16 v9, v13 offset:12616
	v_cvt_pk_bf16_f32 v14, -v108, v59
	ds_write_b16 v9, v14 offset:12872
	v_cvt_pk_bf16_f32 v15, -v109, v59
	ds_write_b16 v9, v15 offset:13128
.Lg1m_done:
	s_mov_b64 s[2:3], 0
	s_branch .LBB0_295
